# final norm: post-norm gain vector loaded once before the row loop
# baseline (speedup 1.0000x reference)
.LBB0_71:
	s_andn2_b64 vcc, exec, s[2:3]
	v_writelane_b32 v255, s44, 0
	s_nop 1
	v_writelane_b32 v255, s45, 1
	v_writelane_b32 v255, s25, 2
	s_cbranch_vccnz .LBB0_424
	s_cmp_eq_u32 s25, 7
	s_cselect_b64 s[76:77], -1, 0
	v_writelane_b32 v255, s76, 3
	s_cmp_lt_i32 s25, 7
	s_nop 0
	v_writelane_b32 v255, s77, 4
	s_cbranch_scc1 .LBB0_79
	s_cmp_gt_i32 s25, 9
	s_cbranch_scc0 .LBB0_93
	s_cmp_gt_i32 s25, 11
	s_cbranch_scc0 .LBB0_111
	s_cmp_gt_i32 s25, 12
	s_mov_b64 s[74:75], -1
	s_cbranch_scc0 .LBB0_112
	s_cmp_eq_u32 s25, 13
	s_cbranch_scc0 .LBB0_120
	s_waitcnt vmcnt(0)
	v_ashrrev_i32_e32 v2, 6, v142
	v_readlane_b32 s0, v254, 0
	v_readlane_b32 s2, v255, 20
	s_nop 3
	s_sub_i32 s3, s0, 0x160
	s_cmp_lg_u32 s2, 0
	s_cselect_b32 s0, s3, s0
	v_add_u32_e32 v18, s0, v2
	s_movk_i32 s0, 0x4100
	v_cmp_gt_i32_e32 vcc, s0, v18
	s_and_saveexec_b64 s[0:1], vcc
	s_cbranch_execz .LBB0_119
	v_lshlrev_b32_e32 v3, 2, v142
	v_and_b32_e32 v4, 0xfc, v3
	v_readlane_b32 s2, v253, 45
	v_lshlrev_b32_e32 v0, 1, v4
	v_readlane_b32 s3, v253, 46
	s_mov_b64 s[20:21], 0
	v_lshlrev_b32_e32 v30, 2, v4
	v_lshl_add_u64 v[20:21], s[2:3], 0, v[0:1]
	v_readlane_b32 s2, v251, 24
	v_readlane_b32 s3, v251, 25
	s_nop 1
	v_lshl_add_u64 v[22:23], s[2:3], 0, v[0:1]
	v_readlane_b32 s2, v251, 9
	v_readlane_b32 s3, v251, 10
	s_nop 1
	v_lshl_add_u64 v[24:25], s[2:3], 0, v[0:1]
	s_movk_i32 s2, 0x80
	v_bfrev_b32_e32 v0, 0.5
	v_bitop3_b32 v33, v3, s2, v0 bitop3:0x6c
	v_bitop3_b32 v60, v3, 64, v0 bitop3:0x6c
	v_bitop3_b32 v61, v3, 32, v0 bitop3:0x6c
	v_bitop3_b32 v62, v3, 16, v0 bitop3:0x6c
	v_bitop3_b32 v63, v3, 8, v0 bitop3:0x6c
	v_bitop3_b32 v64, v3, 4, v0 bitop3:0x6c
	v_lshlrev_b32_e32 v0, 2, v4
	v_lshl_add_u64 v[26:27], s[52:53], 0, v[0:1]
	global_load_dwordx4 v[110:113], v[26:27], off
	global_load_dwordx4 v[114:117], v[26:27], off offset:1024
	global_load_dwordx4 v[122:125], v[26:27], off offset:2048
	global_load_dwordx4 v[126:129], v[26:27], off offset:3072
	v_and_b32_e32 v0, 63, v142
	v_readlane_b32 s2, v253, 62
	v_lshlrev_b32_e32 v0, 3, v0
	v_readlane_b32 s3, v253, 63
	s_nop 1
	v_lshl_add_u64 v[28:29], s[2:3], 0, v[0:1]
	v_readlane_b32 s2, v254, 1
	v_readlane_b32 s3, v255, 20
	s_nop 3
	s_sub_i32 s22, s2, 0x160
	s_cmp_lg_u32 s3, 0
	s_cselect_b32 s2, s22, s2
	v_add_u32_e32 v0, s2, v2
	s_branch .LBB0_81

.LBB0_87:
	s_or_b64 exec, exec, s[2:3]
	v_pk_mul_f32 v[14:15], v[54:55], v[54:55]
	v_pk_mul_f32 v[16:17], v[50:51], v[50:51]
	v_pk_mul_f32 v[10:11], v[56:57], v[56:57]
	v_pk_mul_f32 v[12:13], v[52:53], v[52:53]
	v_mov_b32_e32 v58, v14
	v_mov_b32_e32 v59, v16
	v_mov_b32_e32 v16, v15
	v_pk_add_f32 v[14:15], v[58:59], v[16:17]
	v_mov_b32_e32 v16, v10
	v_mov_b32_e32 v17, v12
	v_pk_mul_f32 v[6:7], v[42:43], v[42:43]
	v_pk_mul_f32 v[8:9], v[46:47], v[46:47]
	v_pk_add_f32 v[14:15], v[16:17], v[14:15]
	v_mov_b32_e32 v12, v11
	v_pk_mul_f32 v[2:3], v[44:45], v[44:45]
	v_pk_mul_f32 v[4:5], v[48:49], v[48:49]
	v_pk_add_f32 v[10:11], v[12:13], v[14:15]
	v_mov_b32_e32 v12, v6
	v_mov_b32_e32 v13, v8
	v_mov_b32_e32 v8, v7
	v_pk_add_f32 v[6:7], v[12:13], v[8:9]
	v_mov_b32_e32 v8, v2
	v_mov_b32_e32 v9, v4
	v_pk_add_f32 v[6:7], v[8:9], v[6:7]
	v_mov_b32_e32 v4, v3
	v_pk_add_f32 v[2:3], v[4:5], v[6:7]
	v_add_f32_e32 v4, v10, v11
	v_add_f32_e32 v3, v3, v4
	v_add_f32_e32 v2, v2, v3
	ds_bpermute_b32 v3, v33, v2
	s_movk_i32 s2, 0x4080
	v_cmp_gt_i32_e32 vcc, s2, v18
	s_mov_b64 s[22:23], 0
	s_waitcnt lgkmcnt(0)
	v_add_f32_e32 v2, v2, v3
	ds_bpermute_b32 v3, v60, v2
	s_waitcnt lgkmcnt(0)
	v_add_f32_e32 v2, v2, v3
	ds_bpermute_b32 v3, v61, v2
	s_waitcnt lgkmcnt(0)
	v_add_f32_e32 v2, v2, v3
	ds_bpermute_b32 v3, v62, v2
	s_waitcnt lgkmcnt(0)
	v_add_f32_e32 v2, v2, v3
	ds_bpermute_b32 v3, v63, v2
	s_waitcnt lgkmcnt(0)
	v_add_f32_e32 v19, v2, v3
	ds_bpermute_b32 v31, v64, v19
	s_and_saveexec_b64 s[2:3], vcc
	s_xor_b64 s[2:3], exec, s[2:3]
	s_cbranch_execz .LBB0_90
	s_mov_b32 s22, 0xfe03f81
	v_mul_hi_i32 v58, v18, s22
	v_lshrrev_b32_e32 v59, 31, v58
	v_ashrrev_i32_e32 v58, 7, v58
	v_add_u32_e32 v58, v58, v59
	s_movk_i32 s22, 0xf7f0
	v_mad_i32_i24 v65, v58, s22, v18
	v_ashrrev_i32_e32 v59, 31, v58
	v_add_u32_e32 v66, -16, v65
	v_mov_b32_e32 v67, v1
	v_lshlrev_b64 v[58:59], 23, v[58:59]
	v_cmp_lt_i32_e32 vcc, 15, v65
	v_lshlrev_b64 v[66:67], 12, v[66:67]
	v_lshl_add_u64 v[58:59], s[60:61], 0, v[58:59]
	v_lshl_add_u64 v[58:59], v[58:59], 0, v[66:67]
	s_and_b64 s[22:23], vcc, exec
	s_andn2_saveexec_b64 s[2:3], s[2:3]
	s_cbranch_execnz .LBB0_91

.LBB0_92:
	s_waitcnt lgkmcnt(0)
	v_add_f32_e32 v19, v19, v31
	v_fmamk_f32 v19, v19, 0x3a800000, v161
	s_mov_b32 s22, 0x800000
	v_mul_f32_e32 v31, 0x4b800000, v19
	v_cmp_gt_f32_e32 vcc, s22, v19
	s_waitcnt vmcnt(7)
	v_lshlrev_b32_e32 v66, 16, v40
	v_and_b32_e32 v67, 0xffff0000, v40
	v_cndmask_b32_e32 v19, v19, v31, vcc
	v_rsq_f32_e32 v19, v19
	v_lshlrev_b32_e32 v40, 16, v41
	v_and_b32_e32 v41, 0xffff0000, v41
	s_waitcnt vmcnt(6)
	v_lshlrev_b32_e32 v68, 16, v38
	v_mul_f32_e32 v31, 0x45800000, v19
	v_cndmask_b32_e32 v19, v19, v31, vcc
	v_mul_f32_e32 v74, 0.5, v19
	v_pk_mul_f32 v[56:57], v[56:57], v[74:75] op_sel_hi:[1,0]
	v_and_b32_e32 v69, 0xffff0000, v38
	s_waitcnt vmcnt(3)
	v_pk_mul_f32 v[16:17], v[112:113], v[56:57]
	v_lshlrev_b32_e32 v38, 16, v39
	v_pk_fma_f32 v[16:17], v[32:33], v[40:41], v[16:17] op_sel_hi:[0,1,1]
	v_pk_mul_f32 v[40:41], v[52:53], v[74:75] op_sel_hi:[1,0]
	v_and_b32_e32 v39, 0xffff0000, v39
	s_waitcnt vmcnt(2)
	v_pk_mul_f32 v[12:13], v[116:117], v[40:41]
	v_lshlrev_b32_e32 v70, 16, v36
	v_pk_fma_f32 v[12:13], v[32:33], v[38:39], v[12:13] op_sel_hi:[0,1,1]
	v_pk_mul_f32 v[38:39], v[48:49], v[74:75] op_sel_hi:[1,0]
	v_and_b32_e32 v71, 0xffff0000, v36
	v_lshlrev_b32_e32 v36, 16, v37
	v_and_b32_e32 v37, 0xffff0000, v37
	s_waitcnt vmcnt(1)
	v_pk_mul_f32 v[8:9], v[124:125], v[38:39]
	v_pk_mul_f32 v[54:55], v[54:55], v[74:75] op_sel_hi:[1,0]
	v_pk_fma_f32 v[8:9], v[32:33], v[36:37], v[8:9] op_sel_hi:[0,1,1]
	v_pk_mul_f32 v[36:37], v[44:45], v[74:75] op_sel_hi:[1,0]
	v_lshlrev_b32_e32 v72, 16, v34
	v_and_b32_e32 v73, 0xffff0000, v34
	v_lshlrev_b32_e32 v34, 16, v35
	v_and_b32_e32 v35, 0xffff0000, v35
	v_pk_mul_f32 v[14:15], v[110:111], v[54:55]
	v_pk_mul_f32 v[50:51], v[50:51], v[74:75] op_sel_hi:[1,0]
	v_pk_mul_f32 v[40:41], v[46:47], v[74:75] op_sel_hi:[1,0]
	v_pk_mul_f32 v[38:39], v[42:43], v[74:75] op_sel_hi:[1,0]
	s_waitcnt vmcnt(0)
	v_pk_mul_f32 v[4:5], v[128:129], v[36:37]
	v_mov_b32_e32 v31, v1
	v_pk_fma_f32 v[14:15], v[32:33], v[66:67], v[14:15] op_sel_hi:[0,1,1]
	v_pk_mul_f32 v[10:11], v[114:115], v[50:51]
	v_pk_mul_f32 v[6:7], v[122:123], v[40:41]
	v_pk_mul_f32 v[2:3], v[126:127], v[38:39]
	v_pk_fma_f32 v[4:5], v[32:33], v[34:35], v[4:5] op_sel_hi:[0,1,1]
	v_lshl_add_u64 v[34:35], v[58:59], 0, v[30:31]
	v_pk_fma_f32 v[10:11], v[32:33], v[68:69], v[10:11] op_sel_hi:[0,1,1]
	v_pk_fma_f32 v[6:7], v[32:33], v[70:71], v[6:7] op_sel_hi:[0,1,1]
	v_pk_fma_f32 v[2:3], v[32:33], v[72:73], v[2:3] op_sel_hi:[0,1,1]
	global_store_dwordx4 v[34:35], v[14:17], off nt
	global_store_dwordx4 v[34:35], v[10:13], off offset:1024 nt
	global_store_dwordx4 v[34:35], v[6:9], off offset:2048 nt
	global_store_dwordx4 v[34:35], v[2:5], off offset:3072 nt
	s_branch .LBB0_80
